# P1+P7 SwiGLU epilogues hand-written: prefetched row sums, packed f32 mul/add, no per-group waits
# speedup vs baseline: 1.0084x; 1.0054x over previous
.LBB0_168:
	s_waitcnt vmcnt(8)
	v_fmamk_f32 v158, v230, 0x3a000000, v156
	v_fmamk_f32 v159, v231, 0x3a000000, v156
	v_fmamk_f32 v160, v232, 0x3a000000, v156
	v_fmamk_f32 v161, v233, 0x3a000000, v156
	v_fmamk_f32 v162, v234, 0x3a000000, v156
	v_fmamk_f32 v163, v235, 0x3a000000, v156
	v_fmamk_f32 v164, v236, 0x3a000000, v156
	v_fmamk_f32 v165, v237, 0x3a000000, v156
	v_rsq_f32_e32 v158, v158
	v_rsq_f32_e32 v159, v159
	v_rsq_f32_e32 v160, v160
	v_rsq_f32_e32 v161, v161
	v_rsq_f32_e32 v162, v162
	v_rsq_f32_e32 v163, v163
	v_rsq_f32_e32 v164, v164
	v_rsq_f32_e32 v165, v165
	v_lshl_add_u32 v144, s2, 8, v150
	v_lshl_or_b32 v146, s3, 7, v152
	v_mul_u32_u24_e32 v145, 0x2c00, v144
	v_lshl_add_u32 v180, v146, 1, v145
	v_add_u32_e32 v181, 0x2c000, v180
	v_add_u32_e32 v182, 0x58000, v180
	v_add_u32_e32 v183, 0x84000, v180
	v_add_u32_e32 v184, 0x160000, v180
	v_add_u32_e32 v185, 0x18c000, v180
	v_add_u32_e32 v186, 0x1b8000, v180
	v_add_u32_e32 v187, 0x1e4000, v180
	v_mov_b32_e32 v176, 0xbfb8aa3b
	s_and_b64 vcc, exec, s[0:1]
	s_cselect_b32 s2, s12, s2
	v_lshl_add_u32 v144, s2, 8, v150
	v_lshlrev_b32_e32 v144, 2, v144
	global_load_dword v230, v144, s[78:79]
	global_load_dword v231, v144, s[78:79] offset:64
	global_load_dword v232, v144, s[78:79] offset:128
	global_load_dword v233, v144, s[78:79] offset:192
	global_load_dword v234, v144, s[78:79] offset:512
	global_load_dword v235, v144, s[78:79] offset:576
	global_load_dword v236, v144, s[78:79] offset:640
	global_load_dword v237, v144, s[78:79] offset:704
	v_pk_mul_f32 v[124:125], v[124:125], v[158:159] op_sel_hi:[1,0]
	v_pk_mul_f32 v[126:127], v[126:127], v[158:159] op_sel_hi:[1,0]
	v_pk_mul_f32 v[116:117], v[116:117], v[158:159] op_sel_hi:[1,0]
	v_pk_mul_f32 v[118:119], v[118:119], v[158:159] op_sel_hi:[1,0]
	v_pk_mul_f32 v[166:167], v[124:125], v[176:177] op_sel_hi:[1,0]
	v_pk_mul_f32 v[168:169], v[126:127], v[176:177] op_sel_hi:[1,0]
	v_pk_mul_f32 v[170:171], v[116:117], v[176:177] op_sel_hi:[1,0]
	v_pk_mul_f32 v[172:173], v[118:119], v[176:177] op_sel_hi:[1,0]
	v_pk_mul_f32 v[120:121], v[120:121], v[158:159] op_sel_hi:[1,0]
	v_pk_mul_f32 v[122:123], v[122:123], v[158:159] op_sel_hi:[1,0]
	v_pk_mul_f32 v[112:113], v[112:113], v[158:159] op_sel_hi:[1,0]
	v_pk_mul_f32 v[114:115], v[114:115], v[158:159] op_sel_hi:[1,0]
	v_exp_f32_e32 v166, v166
	v_exp_f32_e32 v167, v167
	v_exp_f32_e32 v168, v168
	v_exp_f32_e32 v169, v169
	v_exp_f32_e32 v170, v170
	v_exp_f32_e32 v171, v171
	v_exp_f32_e32 v172, v172
	v_exp_f32_e32 v173, v173
	v_pk_add_f32 v[166:167], v[166:167], 1.0 op_sel_hi:[1,0]
	v_pk_add_f32 v[168:169], v[168:169], 1.0 op_sel_hi:[1,0]
	v_pk_add_f32 v[170:171], v[170:171], 1.0 op_sel_hi:[1,0]
	v_pk_add_f32 v[172:173], v[172:173], 1.0 op_sel_hi:[1,0]
	v_rcp_f32_e32 v166, v166
	v_rcp_f32_e32 v167, v167
	v_rcp_f32_e32 v168, v168
	v_rcp_f32_e32 v169, v169
	v_rcp_f32_e32 v170, v170
	v_rcp_f32_e32 v171, v171
	v_rcp_f32_e32 v172, v172
	v_rcp_f32_e32 v173, v173
	v_pk_mul_f32 v[124:125], v[124:125], v[166:167]
	v_pk_mul_f32 v[126:127], v[126:127], v[168:169]
	v_pk_mul_f32 v[116:117], v[116:117], v[170:171]
	v_pk_mul_f32 v[118:119], v[118:119], v[172:173]
	v_pk_mul_f32 v[120:121], v[120:121], v[124:125]
	v_pk_mul_f32 v[122:123], v[122:123], v[126:127]
	v_pk_mul_f32 v[112:113], v[112:113], v[116:117]
	v_pk_mul_f32 v[114:115], v[114:115], v[118:119]
	v_cvt_pk_bf16_f32 v120, v120, v121
	v_cvt_pk_bf16_f32 v121, v122, v123
	v_cvt_pk_bf16_f32 v122, v112, v113
	v_cvt_pk_bf16_f32 v123, v114, v115
	global_store_dwordx4 v180, v[120:123], s[16:17]
	v_pk_mul_f32 v[108:109], v[108:109], v[158:159] op_sel:[0,1] op_sel_hi:[1,1]
	v_pk_mul_f32 v[110:111], v[110:111], v[158:159] op_sel:[0,1] op_sel_hi:[1,1]
	v_pk_mul_f32 v[100:101], v[100:101], v[158:159] op_sel:[0,1] op_sel_hi:[1,1]
	v_pk_mul_f32 v[102:103], v[102:103], v[158:159] op_sel:[0,1] op_sel_hi:[1,1]
	v_pk_mul_f32 v[166:167], v[108:109], v[176:177] op_sel_hi:[1,0]
	v_pk_mul_f32 v[168:169], v[110:111], v[176:177] op_sel_hi:[1,0]
	v_pk_mul_f32 v[170:171], v[100:101], v[176:177] op_sel_hi:[1,0]
	v_pk_mul_f32 v[172:173], v[102:103], v[176:177] op_sel_hi:[1,0]
	v_pk_mul_f32 v[104:105], v[104:105], v[158:159] op_sel:[0,1] op_sel_hi:[1,1]
	v_pk_mul_f32 v[106:107], v[106:107], v[158:159] op_sel:[0,1] op_sel_hi:[1,1]
	v_pk_mul_f32 v[96:97], v[96:97], v[158:159] op_sel:[0,1] op_sel_hi:[1,1]
	v_pk_mul_f32 v[98:99], v[98:99], v[158:159] op_sel:[0,1] op_sel_hi:[1,1]
	v_exp_f32_e32 v166, v166
	v_exp_f32_e32 v167, v167
	v_exp_f32_e32 v168, v168
	v_exp_f32_e32 v169, v169
	v_exp_f32_e32 v170, v170
	v_exp_f32_e32 v171, v171
	v_exp_f32_e32 v172, v172
	v_exp_f32_e32 v173, v173
	v_pk_add_f32 v[166:167], v[166:167], 1.0 op_sel_hi:[1,0]
	v_pk_add_f32 v[168:169], v[168:169], 1.0 op_sel_hi:[1,0]
	v_pk_add_f32 v[170:171], v[170:171], 1.0 op_sel_hi:[1,0]
	v_pk_add_f32 v[172:173], v[172:173], 1.0 op_sel_hi:[1,0]
	v_rcp_f32_e32 v166, v166
	v_rcp_f32_e32 v167, v167
	v_rcp_f32_e32 v168, v168
	v_rcp_f32_e32 v169, v169
	v_rcp_f32_e32 v170, v170
	v_rcp_f32_e32 v171, v171
	v_rcp_f32_e32 v172, v172
	v_rcp_f32_e32 v173, v173
	v_pk_mul_f32 v[108:109], v[108:109], v[166:167]
	v_pk_mul_f32 v[110:111], v[110:111], v[168:169]
	v_pk_mul_f32 v[100:101], v[100:101], v[170:171]
	v_pk_mul_f32 v[102:103], v[102:103], v[172:173]
	v_pk_mul_f32 v[104:105], v[104:105], v[108:109]
	v_pk_mul_f32 v[106:107], v[106:107], v[110:111]
	v_pk_mul_f32 v[96:97], v[96:97], v[100:101]
	v_pk_mul_f32 v[98:99], v[98:99], v[102:103]
	v_cvt_pk_bf16_f32 v104, v104, v105
	v_cvt_pk_bf16_f32 v105, v106, v107
	v_cvt_pk_bf16_f32 v106, v96, v97
	v_cvt_pk_bf16_f32 v107, v98, v99
	global_store_dwordx4 v181, v[104:107], s[16:17]
	v_pk_mul_f32 v[92:93], v[92:93], v[160:161] op_sel_hi:[1,0]
	v_pk_mul_f32 v[94:95], v[94:95], v[160:161] op_sel_hi:[1,0]
	v_pk_mul_f32 v[84:85], v[84:85], v[160:161] op_sel_hi:[1,0]
	v_pk_mul_f32 v[86:87], v[86:87], v[160:161] op_sel_hi:[1,0]
	v_pk_mul_f32 v[166:167], v[92:93], v[176:177] op_sel_hi:[1,0]
	v_pk_mul_f32 v[168:169], v[94:95], v[176:177] op_sel_hi:[1,0]
	v_pk_mul_f32 v[170:171], v[84:85], v[176:177] op_sel_hi:[1,0]
	v_pk_mul_f32 v[172:173], v[86:87], v[176:177] op_sel_hi:[1,0]
	v_pk_mul_f32 v[88:89], v[88:89], v[160:161] op_sel_hi:[1,0]
	v_pk_mul_f32 v[90:91], v[90:91], v[160:161] op_sel_hi:[1,0]
	v_pk_mul_f32 v[80:81], v[80:81], v[160:161] op_sel_hi:[1,0]
	v_pk_mul_f32 v[82:83], v[82:83], v[160:161] op_sel_hi:[1,0]
	v_exp_f32_e32 v166, v166
	v_exp_f32_e32 v167, v167
	v_exp_f32_e32 v168, v168
	v_exp_f32_e32 v169, v169
	v_exp_f32_e32 v170, v170
	v_exp_f32_e32 v171, v171
	v_exp_f32_e32 v172, v172
	v_exp_f32_e32 v173, v173
	v_pk_add_f32 v[166:167], v[166:167], 1.0 op_sel_hi:[1,0]
	v_pk_add_f32 v[168:169], v[168:169], 1.0 op_sel_hi:[1,0]
	v_pk_add_f32 v[170:171], v[170:171], 1.0 op_sel_hi:[1,0]
	v_pk_add_f32 v[172:173], v[172:173], 1.0 op_sel_hi:[1,0]
	v_rcp_f32_e32 v166, v166
	v_rcp_f32_e32 v167, v167
	v_rcp_f32_e32 v168, v168
	v_rcp_f32_e32 v169, v169
	v_rcp_f32_e32 v170, v170
	v_rcp_f32_e32 v171, v171
	v_rcp_f32_e32 v172, v172
	v_rcp_f32_e32 v173, v173
	v_pk_mul_f32 v[92:93], v[92:93], v[166:167]
	v_pk_mul_f32 v[94:95], v[94:95], v[168:169]
	v_pk_mul_f32 v[84:85], v[84:85], v[170:171]
	v_pk_mul_f32 v[86:87], v[86:87], v[172:173]
	v_pk_mul_f32 v[88:89], v[88:89], v[92:93]
	v_pk_mul_f32 v[90:91], v[90:91], v[94:95]
	v_pk_mul_f32 v[80:81], v[80:81], v[84:85]
	v_pk_mul_f32 v[82:83], v[82:83], v[86:87]
	v_cvt_pk_bf16_f32 v88, v88, v89
	v_cvt_pk_bf16_f32 v89, v90, v91
	v_cvt_pk_bf16_f32 v90, v80, v81
	v_cvt_pk_bf16_f32 v91, v82, v83
	global_store_dwordx4 v182, v[88:91], s[16:17]
	v_pk_mul_f32 v[76:77], v[76:77], v[160:161] op_sel:[0,1] op_sel_hi:[1,1]
	v_pk_mul_f32 v[78:79], v[78:79], v[160:161] op_sel:[0,1] op_sel_hi:[1,1]
	v_pk_mul_f32 v[68:69], v[68:69], v[160:161] op_sel:[0,1] op_sel_hi:[1,1]
	v_pk_mul_f32 v[70:71], v[70:71], v[160:161] op_sel:[0,1] op_sel_hi:[1,1]
	v_pk_mul_f32 v[166:167], v[76:77], v[176:177] op_sel_hi:[1,0]
	v_pk_mul_f32 v[168:169], v[78:79], v[176:177] op_sel_hi:[1,0]
	v_pk_mul_f32 v[170:171], v[68:69], v[176:177] op_sel_hi:[1,0]
	v_pk_mul_f32 v[172:173], v[70:71], v[176:177] op_sel_hi:[1,0]
	v_pk_mul_f32 v[72:73], v[72:73], v[160:161] op_sel:[0,1] op_sel_hi:[1,1]
	v_pk_mul_f32 v[74:75], v[74:75], v[160:161] op_sel:[0,1] op_sel_hi:[1,1]
	v_pk_mul_f32 v[64:65], v[64:65], v[160:161] op_sel:[0,1] op_sel_hi:[1,1]
	v_pk_mul_f32 v[66:67], v[66:67], v[160:161] op_sel:[0,1] op_sel_hi:[1,1]
	v_exp_f32_e32 v166, v166
	v_exp_f32_e32 v167, v167
	v_exp_f32_e32 v168, v168
	v_exp_f32_e32 v169, v169
	v_exp_f32_e32 v170, v170
	v_exp_f32_e32 v171, v171
	v_exp_f32_e32 v172, v172
	v_exp_f32_e32 v173, v173
	v_pk_add_f32 v[166:167], v[166:167], 1.0 op_sel_hi:[1,0]
	v_pk_add_f32 v[168:169], v[168:169], 1.0 op_sel_hi:[1,0]
	v_pk_add_f32 v[170:171], v[170:171], 1.0 op_sel_hi:[1,0]
	v_pk_add_f32 v[172:173], v[172:173], 1.0 op_sel_hi:[1,0]
	v_rcp_f32_e32 v166, v166
	v_rcp_f32_e32 v167, v167
	v_rcp_f32_e32 v168, v168
	v_rcp_f32_e32 v169, v169
	v_rcp_f32_e32 v170, v170
	v_rcp_f32_e32 v171, v171
	v_rcp_f32_e32 v172, v172
	v_rcp_f32_e32 v173, v173
	v_pk_mul_f32 v[76:77], v[76:77], v[166:167]
	v_pk_mul_f32 v[78:79], v[78:79], v[168:169]
	v_pk_mul_f32 v[68:69], v[68:69], v[170:171]
	v_pk_mul_f32 v[70:71], v[70:71], v[172:173]
	v_pk_mul_f32 v[72:73], v[72:73], v[76:77]
	v_pk_mul_f32 v[74:75], v[74:75], v[78:79]
	v_pk_mul_f32 v[64:65], v[64:65], v[68:69]
	v_pk_mul_f32 v[66:67], v[66:67], v[70:71]
	v_cvt_pk_bf16_f32 v72, v72, v73
	v_cvt_pk_bf16_f32 v73, v74, v75
	v_cvt_pk_bf16_f32 v74, v64, v65
	v_cvt_pk_bf16_f32 v75, v66, v67
	global_store_dwordx4 v183, v[72:75], s[16:17]
	v_pk_mul_f32 v[60:61], v[60:61], v[162:163] op_sel_hi:[1,0]
	v_pk_mul_f32 v[62:63], v[62:63], v[162:163] op_sel_hi:[1,0]
	v_pk_mul_f32 v[52:53], v[52:53], v[162:163] op_sel_hi:[1,0]
	v_pk_mul_f32 v[54:55], v[54:55], v[162:163] op_sel_hi:[1,0]
	v_pk_mul_f32 v[166:167], v[60:61], v[176:177] op_sel_hi:[1,0]
	v_pk_mul_f32 v[168:169], v[62:63], v[176:177] op_sel_hi:[1,0]
	v_pk_mul_f32 v[170:171], v[52:53], v[176:177] op_sel_hi:[1,0]
	v_pk_mul_f32 v[172:173], v[54:55], v[176:177] op_sel_hi:[1,0]
	v_pk_mul_f32 v[56:57], v[56:57], v[162:163] op_sel_hi:[1,0]
	v_pk_mul_f32 v[58:59], v[58:59], v[162:163] op_sel_hi:[1,0]
	v_pk_mul_f32 v[48:49], v[48:49], v[162:163] op_sel_hi:[1,0]
	v_pk_mul_f32 v[50:51], v[50:51], v[162:163] op_sel_hi:[1,0]
	v_exp_f32_e32 v166, v166
	v_exp_f32_e32 v167, v167
	v_exp_f32_e32 v168, v168
	v_exp_f32_e32 v169, v169
	v_exp_f32_e32 v170, v170
	v_exp_f32_e32 v171, v171
	v_exp_f32_e32 v172, v172
	v_exp_f32_e32 v173, v173
	v_pk_add_f32 v[166:167], v[166:167], 1.0 op_sel_hi:[1,0]
	v_pk_add_f32 v[168:169], v[168:169], 1.0 op_sel_hi:[1,0]
	v_pk_add_f32 v[170:171], v[170:171], 1.0 op_sel_hi:[1,0]
	v_pk_add_f32 v[172:173], v[172:173], 1.0 op_sel_hi:[1,0]
	v_rcp_f32_e32 v166, v166
	v_rcp_f32_e32 v167, v167
	v_rcp_f32_e32 v168, v168
	v_rcp_f32_e32 v169, v169
	v_rcp_f32_e32 v170, v170
	v_rcp_f32_e32 v171, v171
	v_rcp_f32_e32 v172, v172
	v_rcp_f32_e32 v173, v173
	v_pk_mul_f32 v[60:61], v[60:61], v[166:167]
	v_pk_mul_f32 v[62:63], v[62:63], v[168:169]
	v_pk_mul_f32 v[52:53], v[52:53], v[170:171]
	v_pk_mul_f32 v[54:55], v[54:55], v[172:173]
	v_pk_mul_f32 v[56:57], v[56:57], v[60:61]
	v_pk_mul_f32 v[58:59], v[58:59], v[62:63]
	v_pk_mul_f32 v[48:49], v[48:49], v[52:53]
	v_pk_mul_f32 v[50:51], v[50:51], v[54:55]
	v_cvt_pk_bf16_f32 v56, v56, v57
	v_cvt_pk_bf16_f32 v57, v58, v59
	v_cvt_pk_bf16_f32 v58, v48, v49
	v_cvt_pk_bf16_f32 v59, v50, v51
	global_store_dwordx4 v184, v[56:59], s[16:17]
	v_pk_mul_f32 v[44:45], v[44:45], v[162:163] op_sel:[0,1] op_sel_hi:[1,1]
	v_pk_mul_f32 v[46:47], v[46:47], v[162:163] op_sel:[0,1] op_sel_hi:[1,1]
	v_pk_mul_f32 v[36:37], v[36:37], v[162:163] op_sel:[0,1] op_sel_hi:[1,1]
	v_pk_mul_f32 v[38:39], v[38:39], v[162:163] op_sel:[0,1] op_sel_hi:[1,1]
	v_pk_mul_f32 v[166:167], v[44:45], v[176:177] op_sel_hi:[1,0]
	v_pk_mul_f32 v[168:169], v[46:47], v[176:177] op_sel_hi:[1,0]
	v_pk_mul_f32 v[170:171], v[36:37], v[176:177] op_sel_hi:[1,0]
	v_pk_mul_f32 v[172:173], v[38:39], v[176:177] op_sel_hi:[1,0]
	v_pk_mul_f32 v[40:41], v[40:41], v[162:163] op_sel:[0,1] op_sel_hi:[1,1]
	v_pk_mul_f32 v[42:43], v[42:43], v[162:163] op_sel:[0,1] op_sel_hi:[1,1]
	v_pk_mul_f32 v[32:33], v[32:33], v[162:163] op_sel:[0,1] op_sel_hi:[1,1]
	v_pk_mul_f32 v[34:35], v[34:35], v[162:163] op_sel:[0,1] op_sel_hi:[1,1]
	v_exp_f32_e32 v166, v166
	v_exp_f32_e32 v167, v167
	v_exp_f32_e32 v168, v168
	v_exp_f32_e32 v169, v169
	v_exp_f32_e32 v170, v170
	v_exp_f32_e32 v171, v171
	v_exp_f32_e32 v172, v172
	v_exp_f32_e32 v173, v173
	v_pk_add_f32 v[166:167], v[166:167], 1.0 op_sel_hi:[1,0]
	v_pk_add_f32 v[168:169], v[168:169], 1.0 op_sel_hi:[1,0]
	v_pk_add_f32 v[170:171], v[170:171], 1.0 op_sel_hi:[1,0]
	v_pk_add_f32 v[172:173], v[172:173], 1.0 op_sel_hi:[1,0]
	v_rcp_f32_e32 v166, v166
	v_rcp_f32_e32 v167, v167
	v_rcp_f32_e32 v168, v168
	v_rcp_f32_e32 v169, v169
	v_rcp_f32_e32 v170, v170
	v_rcp_f32_e32 v171, v171
	v_rcp_f32_e32 v172, v172
	v_rcp_f32_e32 v173, v173
	v_pk_mul_f32 v[44:45], v[44:45], v[166:167]
	v_pk_mul_f32 v[46:47], v[46:47], v[168:169]
	v_pk_mul_f32 v[36:37], v[36:37], v[170:171]
	v_pk_mul_f32 v[38:39], v[38:39], v[172:173]
	v_pk_mul_f32 v[40:41], v[40:41], v[44:45]
	v_pk_mul_f32 v[42:43], v[42:43], v[46:47]
	v_pk_mul_f32 v[32:33], v[32:33], v[36:37]
	v_pk_mul_f32 v[34:35], v[34:35], v[38:39]
	v_cvt_pk_bf16_f32 v40, v40, v41
	v_cvt_pk_bf16_f32 v41, v42, v43
	v_cvt_pk_bf16_f32 v42, v32, v33
	v_cvt_pk_bf16_f32 v43, v34, v35
	global_store_dwordx4 v185, v[40:43], s[16:17]
	v_pk_mul_f32 v[28:29], v[28:29], v[164:165] op_sel_hi:[1,0]
	v_pk_mul_f32 v[30:31], v[30:31], v[164:165] op_sel_hi:[1,0]
	v_pk_mul_f32 v[20:21], v[20:21], v[164:165] op_sel_hi:[1,0]
	v_pk_mul_f32 v[22:23], v[22:23], v[164:165] op_sel_hi:[1,0]
	v_pk_mul_f32 v[166:167], v[28:29], v[176:177] op_sel_hi:[1,0]
	v_pk_mul_f32 v[168:169], v[30:31], v[176:177] op_sel_hi:[1,0]
	v_pk_mul_f32 v[170:171], v[20:21], v[176:177] op_sel_hi:[1,0]
	v_pk_mul_f32 v[172:173], v[22:23], v[176:177] op_sel_hi:[1,0]
	v_pk_mul_f32 v[24:25], v[24:25], v[164:165] op_sel_hi:[1,0]
	v_pk_mul_f32 v[26:27], v[26:27], v[164:165] op_sel_hi:[1,0]
	v_pk_mul_f32 v[16:17], v[16:17], v[164:165] op_sel_hi:[1,0]
	v_pk_mul_f32 v[18:19], v[18:19], v[164:165] op_sel_hi:[1,0]
	v_exp_f32_e32 v166, v166
	v_exp_f32_e32 v167, v167
	v_exp_f32_e32 v168, v168
	v_exp_f32_e32 v169, v169
	v_exp_f32_e32 v170, v170
	v_exp_f32_e32 v171, v171
	v_exp_f32_e32 v172, v172
	v_exp_f32_e32 v173, v173
	v_pk_add_f32 v[166:167], v[166:167], 1.0 op_sel_hi:[1,0]
	v_pk_add_f32 v[168:169], v[168:169], 1.0 op_sel_hi:[1,0]
	v_pk_add_f32 v[170:171], v[170:171], 1.0 op_sel_hi:[1,0]
	v_pk_add_f32 v[172:173], v[172:173], 1.0 op_sel_hi:[1,0]
	v_rcp_f32_e32 v166, v166
	v_rcp_f32_e32 v167, v167
	v_rcp_f32_e32 v168, v168
	v_rcp_f32_e32 v169, v169
	v_rcp_f32_e32 v170, v170
	v_rcp_f32_e32 v171, v171
	v_rcp_f32_e32 v172, v172
	v_rcp_f32_e32 v173, v173
	v_pk_mul_f32 v[28:29], v[28:29], v[166:167]
	v_pk_mul_f32 v[30:31], v[30:31], v[168:169]
	v_pk_mul_f32 v[20:21], v[20:21], v[170:171]
	v_pk_mul_f32 v[22:23], v[22:23], v[172:173]
	v_pk_mul_f32 v[24:25], v[24:25], v[28:29]
	v_pk_mul_f32 v[26:27], v[26:27], v[30:31]
	v_pk_mul_f32 v[16:17], v[16:17], v[20:21]
	v_pk_mul_f32 v[18:19], v[18:19], v[22:23]
	v_cvt_pk_bf16_f32 v24, v24, v25
	v_cvt_pk_bf16_f32 v25, v26, v27
	v_cvt_pk_bf16_f32 v26, v16, v17
	v_cvt_pk_bf16_f32 v27, v18, v19
	global_store_dwordx4 v186, v[24:27], s[16:17]
	v_pk_mul_f32 v[12:13], v[12:13], v[164:165] op_sel:[0,1] op_sel_hi:[1,1]
	v_pk_mul_f32 v[14:15], v[14:15], v[164:165] op_sel:[0,1] op_sel_hi:[1,1]
	v_pk_mul_f32 v[4:5], v[4:5], v[164:165] op_sel:[0,1] op_sel_hi:[1,1]
	v_pk_mul_f32 v[6:7], v[6:7], v[164:165] op_sel:[0,1] op_sel_hi:[1,1]
	v_pk_mul_f32 v[166:167], v[12:13], v[176:177] op_sel_hi:[1,0]
	v_pk_mul_f32 v[168:169], v[14:15], v[176:177] op_sel_hi:[1,0]
	v_pk_mul_f32 v[170:171], v[4:5], v[176:177] op_sel_hi:[1,0]
	v_pk_mul_f32 v[172:173], v[6:7], v[176:177] op_sel_hi:[1,0]
	v_pk_mul_f32 v[8:9], v[8:9], v[164:165] op_sel:[0,1] op_sel_hi:[1,1]
	v_pk_mul_f32 v[10:11], v[10:11], v[164:165] op_sel:[0,1] op_sel_hi:[1,1]
	v_pk_mul_f32 v[0:1], v[0:1], v[164:165] op_sel:[0,1] op_sel_hi:[1,1]
	v_pk_mul_f32 v[2:3], v[2:3], v[164:165] op_sel:[0,1] op_sel_hi:[1,1]
	v_exp_f32_e32 v166, v166
	v_exp_f32_e32 v167, v167
	v_exp_f32_e32 v168, v168
	v_exp_f32_e32 v169, v169
	v_exp_f32_e32 v170, v170
	v_exp_f32_e32 v171, v171
	v_exp_f32_e32 v172, v172
	v_exp_f32_e32 v173, v173
	v_pk_add_f32 v[166:167], v[166:167], 1.0 op_sel_hi:[1,0]
	v_pk_add_f32 v[168:169], v[168:169], 1.0 op_sel_hi:[1,0]
	v_pk_add_f32 v[170:171], v[170:171], 1.0 op_sel_hi:[1,0]
	v_pk_add_f32 v[172:173], v[172:173], 1.0 op_sel_hi:[1,0]
	v_rcp_f32_e32 v166, v166
	v_rcp_f32_e32 v167, v167
	v_rcp_f32_e32 v168, v168
	v_rcp_f32_e32 v169, v169
	v_rcp_f32_e32 v170, v170
	v_rcp_f32_e32 v171, v171
	v_rcp_f32_e32 v172, v172
	v_rcp_f32_e32 v173, v173
	v_pk_mul_f32 v[12:13], v[12:13], v[166:167]
	v_pk_mul_f32 v[14:15], v[14:15], v[168:169]
	v_pk_mul_f32 v[4:5], v[4:5], v[170:171]
	v_pk_mul_f32 v[6:7], v[6:7], v[172:173]
	v_pk_mul_f32 v[8:9], v[8:9], v[12:13]
	v_pk_mul_f32 v[10:11], v[10:11], v[14:15]
	v_pk_mul_f32 v[0:1], v[0:1], v[4:5]
	v_pk_mul_f32 v[2:3], v[2:3], v[6:7]
	v_cvt_pk_bf16_f32 v8, v8, v9
	v_cvt_pk_bf16_f32 v9, v10, v11
	v_cvt_pk_bf16_f32 v10, v0, v1
	v_cvt_pk_bf16_f32 v11, v2, v3
	s_andn2_b64 vcc, exec, s[0:1]
	s_mov_b64 s[2:3], -1
	global_store_dwordx4 v187, v[8:11], s[16:17]
	s_cbranch_vccnz .LBB0_161
	s_andn2_b64 vcc, exec, s[4:5]
	s_cbranch_vccnz .LBB0_160
	s_barrier
	s_branch .LBB0_160

.LBB0_944:
	s_or_b64 exec, exec, s[2:3]
	v_readlane_b32 s2, v254, 54
	v_mov_b32_e32 v9, v252
	v_readlane_b32 s3, v254, 55
	s_waitcnt lgkmcnt(0)
	s_barrier
	s_andn2_b64 vcc, exec, s[2:3]
	v_readfirstlane_b32 s5, v9
	s_cbranch_vccnz .LBB0_960
	v_lshlrev_b32_e32 v0, 4, v9
	v_add_u32_e32 v1, 0x2000, v0
	v_ashrrev_i32_e32 v2, 31, v1
	v_lshrrev_b32_e32 v2, 22, v2
	v_add_u32_e32 v2, v1, v2
	v_ashrrev_i32_e32 v8, 10, v2
	v_mul_i32_i24_e32 v2, 0x400, v8
	v_sub_u32_e32 v1, v1, v2
	v_lshrrev_b32_e32 v2, 4, v1
	v_bitop3_b32 v1, v2, v1, 32 bitop3:0x6c
	v_ashrrev_i32_e32 v2, 31, v1
	v_lshrrev_b32_e32 v2, 26, v2
	v_add_u32_e32 v2, v1, v2
	v_lshlrev_b32_e32 v3, 3, v8
	v_ashrrev_i32_e32 v10, 6, v2
	v_and_b32_e32 v3, -16, v3
	v_add_u32_e32 v3, v10, v3
	v_and_b32_e32 v4, 3, v10
	s_mov_b32 s2, 0xfffe0
	v_lshrrev_b32_e32 v5, 2, v3
	v_lshlrev_b32_e32 v6, 1, v3
	v_and_b32_e32 v2, 0xc0, v2
	v_and_or_b32 v4, v3, s2, v4
	v_and_b32_e32 v5, 4, v5
	v_and_b32_e32 v6, 24, v6
	v_sub_u32_e32 v1, v1, v2
	v_mov_b32_e32 v2, 1
	v_or3_b32 v4, v4, v5, v6
	v_lshlrev_b32_e32 v5, 5, v8
	v_ashrrev_i16_sdwa v1, v2, sext(v1) dst_sel:DWORD dst_unused:UNUSED_PAD src0_sel:DWORD src1_sel:BYTE_0
	v_and_b32_e32 v5, 32, v5
	v_bfe_i32 v11, v1, 0, 16
	v_add_lshl_u32 v1, v5, v11, 1
	v_lshl_add_u32 v128, v4, 12, v1
	v_lshl_add_u32 v130, v3, 12, v1
	v_bfe_i32 v1, v9, 27, 1
	v_lshrrev_b32_e32 v1, 22, v1
	v_add_u32_e32 v1, v0, v1
	v_and_b32_e32 v1, 0xfffffc00, v1
	v_sub_u32_e32 v0, v0, v1
	v_lshrrev_b32_e32 v1, 4, v0
	v_ashrrev_i32_e32 v3, 31, v9
	v_bitop3_b32 v0, v1, v0, 32 bitop3:0x6c
	v_lshrrev_b32_e32 v3, 26, v3
	v_ashrrev_i32_e32 v1, 31, v0
	v_add_u32_e32 v3, v9, v3
	v_lshrrev_b32_e32 v1, 26, v1
	v_ashrrev_i32_e32 v13, 6, v3
	v_add_u32_e32 v1, v0, v1
	v_lshlrev_b32_e32 v3, 3, v13
	v_ashrrev_i32_e32 v12, 6, v1
	v_and_b32_e32 v3, -16, v3
	v_add_u32_e32 v3, v12, v3
	v_and_b32_e32 v4, 3, v12
	v_and_or_b32 v4, v3, s2, v4
	s_lshr_b32 s2, s81, 29
	s_add_i32 s2, s78, s2
	s_ashr_i32 s8, s5, 6
	s_ashr_i32 s3, s2, 3
	s_and_b32 s2, s2, -8
	s_ashr_i32 s10, s5, 8
	s_lshl_b32 s20, s8, 10
	s_sub_i32 s2, s78, s2
	s_cmp_lt_i32 s2, 0
	s_movk_i32 s21, 0xb1
	s_cselect_b32 s4, s21, 0xb0
	s_mul_i32 s2, s2, s4
	s_add_i32 s2, s2, s3
	s_mul_hi_i32 s3, s2, 0x2e8ba2e9
	s_lshr_b32 s4, s3, 31
	s_ashr_i32 s3, s3, 6
	s_add_i32 s3, s3, s4
	s_lshl_b32 s6, s3, 3
	s_mulk_i32 s3, 0x160
	s_sub_i32 s2, s2, s3
	s_sext_i32_i16 s3, s2
	s_bfe_u32 s3, s3, 0x3001c
	s_add_i32 s3, s2, s3
	s_sext_i32_i16 s4, s3
	s_and_b32 s3, s3, 0xfff8
	s_sub_i32 s2, s2, s3
	s_sext_i32_i16 s2, s2
	v_lshrrev_b32_e32 v5, 2, v3
	v_lshlrev_b32_e32 v6, 1, v3
	v_and_b32_e32 v1, 0xc0, v1
	s_lshr_b32 s4, s4, 3
	s_add_i32 s6, s6, s2
	v_and_b32_e32 v5, 4, v5
	v_and_b32_e32 v6, 24, v6
	v_sub_u32_e32 v0, v0, v1
	s_ashr_i32 s7, s6, 31
	s_bfe_i64 s[12:13], s[4:5], 0x100000
	v_or3_b32 v4, v4, v5, v6
	v_lshlrev_b32_e32 v5, 5, v13
	v_ashrrev_i16_sdwa v0, v2, sext(v0) dst_sel:DWORD dst_unused:UNUSED_PAD src0_sel:DWORD src1_sel:BYTE_0
	s_lshl_b64 s[2:3], s[6:7], 20
	s_lshl_b64 s[12:13], s[12:13], 20
	v_and_b32_e32 v5, 32, v5
	v_bfe_i32 v14, v0, 0, 16
	s_add_u32 s30, s40, s12
	v_add_lshl_u32 v0, v5, v14, 1
	s_addc_u32 s31, s41, s13
	s_add_i32 s22, s20, 0
	v_lshl_add_u32 v132, v4, 12, v0
	v_and_b32_e32 v238, 15, v9
	v_lshl_or_b32 v238, s10, 6, v238
	v_lshl_add_u32 v238, s6, 8, v238
	v_lshlrev_b32_e32 v238, 2, v238
	global_load_dword v230, v238, s[0:1]
	global_load_dword v231, v238, s[0:1] offset:64
	global_load_dword v232, v238, s[0:1] offset:128
	global_load_dword v233, v238, s[0:1] offset:192
	global_load_dword v234, v238, s[0:1] offset:512
	global_load_dword v235, v238, s[0:1] offset:576
	global_load_dword v236, v238, s[0:1] offset:640
	global_load_dword v237, v238, s[0:1] offset:704
	s_add_i32 m0, s22, 0x10000
	v_lshl_add_u32 v134, v3, 12, v0
	global_load_lds_dwordx4 v132, s[30:31]
	s_add_i32 m0, s22, 0x12000
	s_add_u32 s12, s30, 0x80000
	global_load_lds_dwordx4 v128, s[30:31]
	s_addc_u32 s13, s31, 0
	s_add_i32 m0, s22, 0x14000
	v_mov_b32_e32 v133, 0
	global_load_lds_dwordx4 v132, s[12:13]
	s_add_i32 m0, s22, 0x16000
	s_add_u32 s28, s18, s2
	s_addc_u32 s29, s19, s3
	s_add_i32 s23, s22, 0x2000
	global_load_lds_dwordx4 v128, s[12:13]
	s_mov_b32 m0, s22
	s_add_u32 s2, s28, 0x80000
	global_load_lds_dwordx4 v134, s[28:29]
	s_mov_b32 m0, s23
	s_addc_u32 s3, s29, 0
	s_add_i32 s33, s22, 0x4000
	global_load_lds_dwordx4 v130, s[28:29]
	s_mov_b32 m0, s33
	s_add_i32 s35, s22, 0x6000
	global_load_lds_dwordx4 v134, s[2:3]
	s_mov_b32 m0, s35
	v_mov_b32_e32 v129, v133
	global_load_lds_dwordx4 v130, s[2:3]
	v_mov_b32_e32 v135, v133
	v_mov_b32_e32 v131, v133
	s_cmp_eq_u32 s10, 1
	s_mov_b32 s36, 0
	v_lshl_add_u64 v[6:7], s[30:31], 0, v[132:133]
	v_lshl_add_u64 v[4:5], s[30:31], 0, v[128:129]
	v_lshl_add_u64 v[0:1], s[28:29], 0, v[134:135]
	s_cselect_b64 s[2:3], -1, 0
	s_cmp_lg_u32 s10, 1
	v_lshl_add_u64 v[2:3], s[28:29], 0, v[130:131]
	s_cbranch_scc1 .LBB0_947
	s_barrier

.LBB0_956:
	s_waitcnt vmcnt(8)
	v_fmamk_f32 v158, v230, 0x3a000000, v154
	v_fmamk_f32 v159, v231, 0x3a000000, v154
	v_fmamk_f32 v160, v232, 0x3a000000, v154
	v_fmamk_f32 v161, v233, 0x3a000000, v154
	v_fmamk_f32 v162, v234, 0x3a000000, v154
	v_fmamk_f32 v163, v235, 0x3a000000, v154
	v_fmamk_f32 v164, v236, 0x3a000000, v154
	v_fmamk_f32 v165, v237, 0x3a000000, v154
	v_rsq_f32_e32 v158, v158
	v_rsq_f32_e32 v159, v159
	v_rsq_f32_e32 v160, v160
	v_rsq_f32_e32 v161, v161
	v_rsq_f32_e32 v162, v162
	v_rsq_f32_e32 v163, v163
	v_rsq_f32_e32 v164, v164
	v_rsq_f32_e32 v165, v165
	v_lshl_add_u32 v144, s6, 8, v148
	v_lshl_or_b32 v146, s7, 7, v150
	v_mul_u32_u24_e32 v145, 0x2c00, v144
	v_lshl_add_u32 v180, v146, 1, v145
	v_add_u32_e32 v181, 0x2c000, v180
	v_add_u32_e32 v182, 0x58000, v180
	v_add_u32_e32 v183, 0x84000, v180
	v_add_u32_e32 v184, 0x160000, v180
	v_add_u32_e32 v185, 0x18c000, v180
	v_add_u32_e32 v186, 0x1b8000, v180
	v_add_u32_e32 v187, 0x1e4000, v180
	v_mov_b32_e32 v176, 0xbfb8aa3b
	s_and_b64 vcc, exec, s[4:5]
	s_cselect_b32 s6, s14, s6
	v_lshl_add_u32 v144, s6, 8, v148
	v_lshlrev_b32_e32 v144, 2, v144
	global_load_dword v230, v144, s[0:1]
	global_load_dword v231, v144, s[0:1] offset:64
	global_load_dword v232, v144, s[0:1] offset:128
	global_load_dword v233, v144, s[0:1] offset:192
	global_load_dword v234, v144, s[0:1] offset:512
	global_load_dword v235, v144, s[0:1] offset:576
	global_load_dword v236, v144, s[0:1] offset:640
	global_load_dword v237, v144, s[0:1] offset:704
	v_pk_mul_f32 v[116:117], v[116:117], v[158:159] op_sel_hi:[1,0]
	v_pk_mul_f32 v[118:119], v[118:119], v[158:159] op_sel_hi:[1,0]
	v_pk_mul_f32 v[112:113], v[112:113], v[158:159] op_sel_hi:[1,0]
	v_pk_mul_f32 v[114:115], v[114:115], v[158:159] op_sel_hi:[1,0]
	v_pk_mul_f32 v[166:167], v[116:117], v[176:177] op_sel_hi:[1,0]
	v_pk_mul_f32 v[168:169], v[118:119], v[176:177] op_sel_hi:[1,0]
	v_pk_mul_f32 v[170:171], v[112:113], v[176:177] op_sel_hi:[1,0]
	v_pk_mul_f32 v[172:173], v[114:115], v[176:177] op_sel_hi:[1,0]
	v_pk_mul_f32 v[124:125], v[124:125], v[158:159] op_sel_hi:[1,0]
	v_pk_mul_f32 v[126:127], v[126:127], v[158:159] op_sel_hi:[1,0]
	v_pk_mul_f32 v[120:121], v[120:121], v[158:159] op_sel_hi:[1,0]
	v_pk_mul_f32 v[122:123], v[122:123], v[158:159] op_sel_hi:[1,0]
	v_exp_f32_e32 v166, v166
	v_exp_f32_e32 v167, v167
	v_exp_f32_e32 v168, v168
	v_exp_f32_e32 v169, v169
	v_exp_f32_e32 v170, v170
	v_exp_f32_e32 v171, v171
	v_exp_f32_e32 v172, v172
	v_exp_f32_e32 v173, v173
	v_pk_add_f32 v[166:167], v[166:167], 1.0 op_sel_hi:[1,0]
	v_pk_add_f32 v[168:169], v[168:169], 1.0 op_sel_hi:[1,0]
	v_pk_add_f32 v[170:171], v[170:171], 1.0 op_sel_hi:[1,0]
	v_pk_add_f32 v[172:173], v[172:173], 1.0 op_sel_hi:[1,0]
	v_rcp_f32_e32 v166, v166
	v_rcp_f32_e32 v167, v167
	v_rcp_f32_e32 v168, v168
	v_rcp_f32_e32 v169, v169
	v_rcp_f32_e32 v170, v170
	v_rcp_f32_e32 v171, v171
	v_rcp_f32_e32 v172, v172
	v_rcp_f32_e32 v173, v173
	v_pk_mul_f32 v[116:117], v[116:117], v[166:167]
	v_pk_mul_f32 v[118:119], v[118:119], v[168:169]
	v_pk_mul_f32 v[112:113], v[112:113], v[170:171]
	v_pk_mul_f32 v[114:115], v[114:115], v[172:173]
	v_pk_mul_f32 v[124:125], v[124:125], v[116:117]
	v_pk_mul_f32 v[126:127], v[126:127], v[118:119]
	v_pk_mul_f32 v[120:121], v[120:121], v[112:113]
	v_pk_mul_f32 v[122:123], v[122:123], v[114:115]
	v_cvt_pk_bf16_f32 v124, v124, v125
	v_cvt_pk_bf16_f32 v125, v126, v127
	v_cvt_pk_bf16_f32 v126, v120, v121
	v_cvt_pk_bf16_f32 v127, v122, v123
	global_store_dwordx4 v180, v[124:127], s[16:17]
	v_pk_mul_f32 v[100:101], v[100:101], v[158:159] op_sel:[0,1] op_sel_hi:[1,1]
	v_pk_mul_f32 v[102:103], v[102:103], v[158:159] op_sel:[0,1] op_sel_hi:[1,1]
	v_pk_mul_f32 v[96:97], v[96:97], v[158:159] op_sel:[0,1] op_sel_hi:[1,1]
	v_pk_mul_f32 v[98:99], v[98:99], v[158:159] op_sel:[0,1] op_sel_hi:[1,1]
	v_pk_mul_f32 v[166:167], v[100:101], v[176:177] op_sel_hi:[1,0]
	v_pk_mul_f32 v[168:169], v[102:103], v[176:177] op_sel_hi:[1,0]
	v_pk_mul_f32 v[170:171], v[96:97], v[176:177] op_sel_hi:[1,0]
	v_pk_mul_f32 v[172:173], v[98:99], v[176:177] op_sel_hi:[1,0]
	v_pk_mul_f32 v[108:109], v[108:109], v[158:159] op_sel:[0,1] op_sel_hi:[1,1]
	v_pk_mul_f32 v[110:111], v[110:111], v[158:159] op_sel:[0,1] op_sel_hi:[1,1]
	v_pk_mul_f32 v[104:105], v[104:105], v[158:159] op_sel:[0,1] op_sel_hi:[1,1]
	v_pk_mul_f32 v[106:107], v[106:107], v[158:159] op_sel:[0,1] op_sel_hi:[1,1]
	v_exp_f32_e32 v166, v166
	v_exp_f32_e32 v167, v167
	v_exp_f32_e32 v168, v168
	v_exp_f32_e32 v169, v169
	v_exp_f32_e32 v170, v170
	v_exp_f32_e32 v171, v171
	v_exp_f32_e32 v172, v172
	v_exp_f32_e32 v173, v173
	v_pk_add_f32 v[166:167], v[166:167], 1.0 op_sel_hi:[1,0]
	v_pk_add_f32 v[168:169], v[168:169], 1.0 op_sel_hi:[1,0]
	v_pk_add_f32 v[170:171], v[170:171], 1.0 op_sel_hi:[1,0]
	v_pk_add_f32 v[172:173], v[172:173], 1.0 op_sel_hi:[1,0]
	v_rcp_f32_e32 v166, v166
	v_rcp_f32_e32 v167, v167
	v_rcp_f32_e32 v168, v168
	v_rcp_f32_e32 v169, v169
	v_rcp_f32_e32 v170, v170
	v_rcp_f32_e32 v171, v171
	v_rcp_f32_e32 v172, v172
	v_rcp_f32_e32 v173, v173
	v_pk_mul_f32 v[100:101], v[100:101], v[166:167]
	v_pk_mul_f32 v[102:103], v[102:103], v[168:169]
	v_pk_mul_f32 v[96:97], v[96:97], v[170:171]
	v_pk_mul_f32 v[98:99], v[98:99], v[172:173]
	v_pk_mul_f32 v[108:109], v[108:109], v[100:101]
	v_pk_mul_f32 v[110:111], v[110:111], v[102:103]
	v_pk_mul_f32 v[104:105], v[104:105], v[96:97]
	v_pk_mul_f32 v[106:107], v[106:107], v[98:99]
	v_cvt_pk_bf16_f32 v108, v108, v109
	v_cvt_pk_bf16_f32 v109, v110, v111
	v_cvt_pk_bf16_f32 v110, v104, v105
	v_cvt_pk_bf16_f32 v111, v106, v107
	global_store_dwordx4 v181, v[108:111], s[16:17]
	v_pk_mul_f32 v[84:85], v[84:85], v[160:161] op_sel_hi:[1,0]
	v_pk_mul_f32 v[86:87], v[86:87], v[160:161] op_sel_hi:[1,0]
	v_pk_mul_f32 v[80:81], v[80:81], v[160:161] op_sel_hi:[1,0]
	v_pk_mul_f32 v[82:83], v[82:83], v[160:161] op_sel_hi:[1,0]
	v_pk_mul_f32 v[166:167], v[84:85], v[176:177] op_sel_hi:[1,0]
	v_pk_mul_f32 v[168:169], v[86:87], v[176:177] op_sel_hi:[1,0]
	v_pk_mul_f32 v[170:171], v[80:81], v[176:177] op_sel_hi:[1,0]
	v_pk_mul_f32 v[172:173], v[82:83], v[176:177] op_sel_hi:[1,0]
	v_pk_mul_f32 v[92:93], v[92:93], v[160:161] op_sel_hi:[1,0]
	v_pk_mul_f32 v[94:95], v[94:95], v[160:161] op_sel_hi:[1,0]
	v_pk_mul_f32 v[88:89], v[88:89], v[160:161] op_sel_hi:[1,0]
	v_pk_mul_f32 v[90:91], v[90:91], v[160:161] op_sel_hi:[1,0]
	v_exp_f32_e32 v166, v166
	v_exp_f32_e32 v167, v167
	v_exp_f32_e32 v168, v168
	v_exp_f32_e32 v169, v169
	v_exp_f32_e32 v170, v170
	v_exp_f32_e32 v171, v171
	v_exp_f32_e32 v172, v172
	v_exp_f32_e32 v173, v173
	v_pk_add_f32 v[166:167], v[166:167], 1.0 op_sel_hi:[1,0]
	v_pk_add_f32 v[168:169], v[168:169], 1.0 op_sel_hi:[1,0]
	v_pk_add_f32 v[170:171], v[170:171], 1.0 op_sel_hi:[1,0]
	v_pk_add_f32 v[172:173], v[172:173], 1.0 op_sel_hi:[1,0]
	v_rcp_f32_e32 v166, v166
	v_rcp_f32_e32 v167, v167
	v_rcp_f32_e32 v168, v168
	v_rcp_f32_e32 v169, v169
	v_rcp_f32_e32 v170, v170
	v_rcp_f32_e32 v171, v171
	v_rcp_f32_e32 v172, v172
	v_rcp_f32_e32 v173, v173
	v_pk_mul_f32 v[84:85], v[84:85], v[166:167]
	v_pk_mul_f32 v[86:87], v[86:87], v[168:169]
	v_pk_mul_f32 v[80:81], v[80:81], v[170:171]
	v_pk_mul_f32 v[82:83], v[82:83], v[172:173]
	v_pk_mul_f32 v[92:93], v[92:93], v[84:85]
	v_pk_mul_f32 v[94:95], v[94:95], v[86:87]
	v_pk_mul_f32 v[88:89], v[88:89], v[80:81]
	v_pk_mul_f32 v[90:91], v[90:91], v[82:83]
	v_cvt_pk_bf16_f32 v92, v92, v93
	v_cvt_pk_bf16_f32 v93, v94, v95
	v_cvt_pk_bf16_f32 v94, v88, v89
	v_cvt_pk_bf16_f32 v95, v90, v91
	global_store_dwordx4 v182, v[92:95], s[16:17]
	v_pk_mul_f32 v[72:73], v[72:73], v[160:161] op_sel:[0,1] op_sel_hi:[1,1]
	v_pk_mul_f32 v[74:75], v[74:75], v[160:161] op_sel:[0,1] op_sel_hi:[1,1]
	v_pk_mul_f32 v[64:65], v[64:65], v[160:161] op_sel:[0,1] op_sel_hi:[1,1]
	v_pk_mul_f32 v[66:67], v[66:67], v[160:161] op_sel:[0,1] op_sel_hi:[1,1]
	v_pk_mul_f32 v[166:167], v[72:73], v[176:177] op_sel_hi:[1,0]
	v_pk_mul_f32 v[168:169], v[74:75], v[176:177] op_sel_hi:[1,0]
	v_pk_mul_f32 v[170:171], v[64:65], v[176:177] op_sel_hi:[1,0]
	v_pk_mul_f32 v[172:173], v[66:67], v[176:177] op_sel_hi:[1,0]
	v_pk_mul_f32 v[76:77], v[76:77], v[160:161] op_sel:[0,1] op_sel_hi:[1,1]
	v_pk_mul_f32 v[78:79], v[78:79], v[160:161] op_sel:[0,1] op_sel_hi:[1,1]
	v_pk_mul_f32 v[68:69], v[68:69], v[160:161] op_sel:[0,1] op_sel_hi:[1,1]
	v_pk_mul_f32 v[70:71], v[70:71], v[160:161] op_sel:[0,1] op_sel_hi:[1,1]
	v_exp_f32_e32 v166, v166
	v_exp_f32_e32 v167, v167
	v_exp_f32_e32 v168, v168
	v_exp_f32_e32 v169, v169
	v_exp_f32_e32 v170, v170
	v_exp_f32_e32 v171, v171
	v_exp_f32_e32 v172, v172
	v_exp_f32_e32 v173, v173
	v_pk_add_f32 v[166:167], v[166:167], 1.0 op_sel_hi:[1,0]
	v_pk_add_f32 v[168:169], v[168:169], 1.0 op_sel_hi:[1,0]
	v_pk_add_f32 v[170:171], v[170:171], 1.0 op_sel_hi:[1,0]
	v_pk_add_f32 v[172:173], v[172:173], 1.0 op_sel_hi:[1,0]
	v_rcp_f32_e32 v166, v166
	v_rcp_f32_e32 v167, v167
	v_rcp_f32_e32 v168, v168
	v_rcp_f32_e32 v169, v169
	v_rcp_f32_e32 v170, v170
	v_rcp_f32_e32 v171, v171
	v_rcp_f32_e32 v172, v172
	v_rcp_f32_e32 v173, v173
	v_pk_mul_f32 v[72:73], v[72:73], v[166:167]
	v_pk_mul_f32 v[74:75], v[74:75], v[168:169]
	v_pk_mul_f32 v[64:65], v[64:65], v[170:171]
	v_pk_mul_f32 v[66:67], v[66:67], v[172:173]
	v_pk_mul_f32 v[76:77], v[76:77], v[72:73]
	v_pk_mul_f32 v[78:79], v[78:79], v[74:75]
	v_pk_mul_f32 v[68:69], v[68:69], v[64:65]
	v_pk_mul_f32 v[70:71], v[70:71], v[66:67]
	v_cvt_pk_bf16_f32 v76, v76, v77
	v_cvt_pk_bf16_f32 v77, v78, v79
	v_cvt_pk_bf16_f32 v78, v68, v69
	v_cvt_pk_bf16_f32 v79, v70, v71
	global_store_dwordx4 v183, v[76:79], s[16:17]
	v_pk_mul_f32 v[56:57], v[56:57], v[162:163] op_sel_hi:[1,0]
	v_pk_mul_f32 v[58:59], v[58:59], v[162:163] op_sel_hi:[1,0]
	v_pk_mul_f32 v[48:49], v[48:49], v[162:163] op_sel_hi:[1,0]
	v_pk_mul_f32 v[50:51], v[50:51], v[162:163] op_sel_hi:[1,0]
	v_pk_mul_f32 v[166:167], v[56:57], v[176:177] op_sel_hi:[1,0]
	v_pk_mul_f32 v[168:169], v[58:59], v[176:177] op_sel_hi:[1,0]
	v_pk_mul_f32 v[170:171], v[48:49], v[176:177] op_sel_hi:[1,0]
	v_pk_mul_f32 v[172:173], v[50:51], v[176:177] op_sel_hi:[1,0]
	v_pk_mul_f32 v[60:61], v[60:61], v[162:163] op_sel_hi:[1,0]
	v_pk_mul_f32 v[62:63], v[62:63], v[162:163] op_sel_hi:[1,0]
	v_pk_mul_f32 v[52:53], v[52:53], v[162:163] op_sel_hi:[1,0]
	v_pk_mul_f32 v[54:55], v[54:55], v[162:163] op_sel_hi:[1,0]
	v_exp_f32_e32 v166, v166
	v_exp_f32_e32 v167, v167
	v_exp_f32_e32 v168, v168
	v_exp_f32_e32 v169, v169
	v_exp_f32_e32 v170, v170
	v_exp_f32_e32 v171, v171
	v_exp_f32_e32 v172, v172
	v_exp_f32_e32 v173, v173
	v_pk_add_f32 v[166:167], v[166:167], 1.0 op_sel_hi:[1,0]
	v_pk_add_f32 v[168:169], v[168:169], 1.0 op_sel_hi:[1,0]
	v_pk_add_f32 v[170:171], v[170:171], 1.0 op_sel_hi:[1,0]
	v_pk_add_f32 v[172:173], v[172:173], 1.0 op_sel_hi:[1,0]
	v_rcp_f32_e32 v166, v166
	v_rcp_f32_e32 v167, v167
	v_rcp_f32_e32 v168, v168
	v_rcp_f32_e32 v169, v169
	v_rcp_f32_e32 v170, v170
	v_rcp_f32_e32 v171, v171
	v_rcp_f32_e32 v172, v172
	v_rcp_f32_e32 v173, v173
	v_pk_mul_f32 v[56:57], v[56:57], v[166:167]
	v_pk_mul_f32 v[58:59], v[58:59], v[168:169]
	v_pk_mul_f32 v[48:49], v[48:49], v[170:171]
	v_pk_mul_f32 v[50:51], v[50:51], v[172:173]
	v_pk_mul_f32 v[60:61], v[60:61], v[56:57]
	v_pk_mul_f32 v[62:63], v[62:63], v[58:59]
	v_pk_mul_f32 v[52:53], v[52:53], v[48:49]
	v_pk_mul_f32 v[54:55], v[54:55], v[50:51]
	v_cvt_pk_bf16_f32 v60, v60, v61
	v_cvt_pk_bf16_f32 v61, v62, v63
	v_cvt_pk_bf16_f32 v62, v52, v53
	v_cvt_pk_bf16_f32 v63, v54, v55
	global_store_dwordx4 v184, v[60:63], s[16:17]
	v_pk_mul_f32 v[40:41], v[40:41], v[162:163] op_sel:[0,1] op_sel_hi:[1,1]
	v_pk_mul_f32 v[42:43], v[42:43], v[162:163] op_sel:[0,1] op_sel_hi:[1,1]
	v_pk_mul_f32 v[32:33], v[32:33], v[162:163] op_sel:[0,1] op_sel_hi:[1,1]
	v_pk_mul_f32 v[34:35], v[34:35], v[162:163] op_sel:[0,1] op_sel_hi:[1,1]
	v_pk_mul_f32 v[166:167], v[40:41], v[176:177] op_sel_hi:[1,0]
	v_pk_mul_f32 v[168:169], v[42:43], v[176:177] op_sel_hi:[1,0]
	v_pk_mul_f32 v[170:171], v[32:33], v[176:177] op_sel_hi:[1,0]
	v_pk_mul_f32 v[172:173], v[34:35], v[176:177] op_sel_hi:[1,0]
	v_pk_mul_f32 v[44:45], v[44:45], v[162:163] op_sel:[0,1] op_sel_hi:[1,1]
	v_pk_mul_f32 v[46:47], v[46:47], v[162:163] op_sel:[0,1] op_sel_hi:[1,1]
	v_pk_mul_f32 v[36:37], v[36:37], v[162:163] op_sel:[0,1] op_sel_hi:[1,1]
	v_pk_mul_f32 v[38:39], v[38:39], v[162:163] op_sel:[0,1] op_sel_hi:[1,1]
	v_exp_f32_e32 v166, v166
	v_exp_f32_e32 v167, v167
	v_exp_f32_e32 v168, v168
	v_exp_f32_e32 v169, v169
	v_exp_f32_e32 v170, v170
	v_exp_f32_e32 v171, v171
	v_exp_f32_e32 v172, v172
	v_exp_f32_e32 v173, v173
	v_pk_add_f32 v[166:167], v[166:167], 1.0 op_sel_hi:[1,0]
	v_pk_add_f32 v[168:169], v[168:169], 1.0 op_sel_hi:[1,0]
	v_pk_add_f32 v[170:171], v[170:171], 1.0 op_sel_hi:[1,0]
	v_pk_add_f32 v[172:173], v[172:173], 1.0 op_sel_hi:[1,0]
	v_rcp_f32_e32 v166, v166
	v_rcp_f32_e32 v167, v167
	v_rcp_f32_e32 v168, v168
	v_rcp_f32_e32 v169, v169
	v_rcp_f32_e32 v170, v170
	v_rcp_f32_e32 v171, v171
	v_rcp_f32_e32 v172, v172
	v_rcp_f32_e32 v173, v173
	v_pk_mul_f32 v[40:41], v[40:41], v[166:167]
	v_pk_mul_f32 v[42:43], v[42:43], v[168:169]
	v_pk_mul_f32 v[32:33], v[32:33], v[170:171]
	v_pk_mul_f32 v[34:35], v[34:35], v[172:173]
	v_pk_mul_f32 v[44:45], v[44:45], v[40:41]
	v_pk_mul_f32 v[46:47], v[46:47], v[42:43]
	v_pk_mul_f32 v[36:37], v[36:37], v[32:33]
	v_pk_mul_f32 v[38:39], v[38:39], v[34:35]
	v_cvt_pk_bf16_f32 v44, v44, v45
	v_cvt_pk_bf16_f32 v45, v46, v47
	v_cvt_pk_bf16_f32 v46, v36, v37
	v_cvt_pk_bf16_f32 v47, v38, v39
	global_store_dwordx4 v185, v[44:47], s[16:17]
	v_pk_mul_f32 v[24:25], v[24:25], v[164:165] op_sel_hi:[1,0]
	v_pk_mul_f32 v[26:27], v[26:27], v[164:165] op_sel_hi:[1,0]
	v_pk_mul_f32 v[16:17], v[16:17], v[164:165] op_sel_hi:[1,0]
	v_pk_mul_f32 v[18:19], v[18:19], v[164:165] op_sel_hi:[1,0]
	v_pk_mul_f32 v[166:167], v[24:25], v[176:177] op_sel_hi:[1,0]
	v_pk_mul_f32 v[168:169], v[26:27], v[176:177] op_sel_hi:[1,0]
	v_pk_mul_f32 v[170:171], v[16:17], v[176:177] op_sel_hi:[1,0]
	v_pk_mul_f32 v[172:173], v[18:19], v[176:177] op_sel_hi:[1,0]
	v_pk_mul_f32 v[28:29], v[28:29], v[164:165] op_sel_hi:[1,0]
	v_pk_mul_f32 v[30:31], v[30:31], v[164:165] op_sel_hi:[1,0]
	v_pk_mul_f32 v[20:21], v[20:21], v[164:165] op_sel_hi:[1,0]
	v_pk_mul_f32 v[22:23], v[22:23], v[164:165] op_sel_hi:[1,0]
	v_exp_f32_e32 v166, v166
	v_exp_f32_e32 v167, v167
	v_exp_f32_e32 v168, v168
	v_exp_f32_e32 v169, v169
	v_exp_f32_e32 v170, v170
	v_exp_f32_e32 v171, v171
	v_exp_f32_e32 v172, v172
	v_exp_f32_e32 v173, v173
	v_pk_add_f32 v[166:167], v[166:167], 1.0 op_sel_hi:[1,0]
	v_pk_add_f32 v[168:169], v[168:169], 1.0 op_sel_hi:[1,0]
	v_pk_add_f32 v[170:171], v[170:171], 1.0 op_sel_hi:[1,0]
	v_pk_add_f32 v[172:173], v[172:173], 1.0 op_sel_hi:[1,0]
	v_rcp_f32_e32 v166, v166
	v_rcp_f32_e32 v167, v167
	v_rcp_f32_e32 v168, v168
	v_rcp_f32_e32 v169, v169
	v_rcp_f32_e32 v170, v170
	v_rcp_f32_e32 v171, v171
	v_rcp_f32_e32 v172, v172
	v_rcp_f32_e32 v173, v173
	v_pk_mul_f32 v[24:25], v[24:25], v[166:167]
	v_pk_mul_f32 v[26:27], v[26:27], v[168:169]
	v_pk_mul_f32 v[16:17], v[16:17], v[170:171]
	v_pk_mul_f32 v[18:19], v[18:19], v[172:173]
	v_pk_mul_f32 v[28:29], v[28:29], v[24:25]
	v_pk_mul_f32 v[30:31], v[30:31], v[26:27]
	v_pk_mul_f32 v[20:21], v[20:21], v[16:17]
	v_pk_mul_f32 v[22:23], v[22:23], v[18:19]
	v_cvt_pk_bf16_f32 v28, v28, v29
	v_cvt_pk_bf16_f32 v29, v30, v31
	v_cvt_pk_bf16_f32 v30, v20, v21
	v_cvt_pk_bf16_f32 v31, v22, v23
	global_store_dwordx4 v186, v[28:31], s[16:17]
	v_pk_mul_f32 v[8:9], v[8:9], v[164:165] op_sel:[0,1] op_sel_hi:[1,1]
	v_pk_mul_f32 v[10:11], v[10:11], v[164:165] op_sel:[0,1] op_sel_hi:[1,1]
	v_pk_mul_f32 v[0:1], v[0:1], v[164:165] op_sel:[0,1] op_sel_hi:[1,1]
	v_pk_mul_f32 v[2:3], v[2:3], v[164:165] op_sel:[0,1] op_sel_hi:[1,1]
	v_pk_mul_f32 v[166:167], v[8:9], v[176:177] op_sel_hi:[1,0]
	v_pk_mul_f32 v[168:169], v[10:11], v[176:177] op_sel_hi:[1,0]
	v_pk_mul_f32 v[170:171], v[0:1], v[176:177] op_sel_hi:[1,0]
	v_pk_mul_f32 v[172:173], v[2:3], v[176:177] op_sel_hi:[1,0]
	v_pk_mul_f32 v[12:13], v[12:13], v[164:165] op_sel:[0,1] op_sel_hi:[1,1]
	v_pk_mul_f32 v[14:15], v[14:15], v[164:165] op_sel:[0,1] op_sel_hi:[1,1]
	v_pk_mul_f32 v[4:5], v[4:5], v[164:165] op_sel:[0,1] op_sel_hi:[1,1]
	v_pk_mul_f32 v[6:7], v[6:7], v[164:165] op_sel:[0,1] op_sel_hi:[1,1]
	v_exp_f32_e32 v166, v166
	v_exp_f32_e32 v167, v167
	v_exp_f32_e32 v168, v168
	v_exp_f32_e32 v169, v169
	v_exp_f32_e32 v170, v170
	v_exp_f32_e32 v171, v171
	v_exp_f32_e32 v172, v172
	v_exp_f32_e32 v173, v173
	v_pk_add_f32 v[166:167], v[166:167], 1.0 op_sel_hi:[1,0]
	v_pk_add_f32 v[168:169], v[168:169], 1.0 op_sel_hi:[1,0]
	v_pk_add_f32 v[170:171], v[170:171], 1.0 op_sel_hi:[1,0]
	v_pk_add_f32 v[172:173], v[172:173], 1.0 op_sel_hi:[1,0]
	v_rcp_f32_e32 v166, v166
	v_rcp_f32_e32 v167, v167
	v_rcp_f32_e32 v168, v168
	v_rcp_f32_e32 v169, v169
	v_rcp_f32_e32 v170, v170
	v_rcp_f32_e32 v171, v171
	v_rcp_f32_e32 v172, v172
	v_rcp_f32_e32 v173, v173
	v_pk_mul_f32 v[8:9], v[8:9], v[166:167]
	v_pk_mul_f32 v[10:11], v[10:11], v[168:169]
	v_pk_mul_f32 v[0:1], v[0:1], v[170:171]
	v_pk_mul_f32 v[2:3], v[2:3], v[172:173]
	v_pk_mul_f32 v[12:13], v[12:13], v[8:9]
	v_pk_mul_f32 v[14:15], v[14:15], v[10:11]
	v_pk_mul_f32 v[4:5], v[4:5], v[0:1]
	v_pk_mul_f32 v[6:7], v[6:7], v[2:3]
	v_cvt_pk_bf16_f32 v12, v12, v13
	v_cvt_pk_bf16_f32 v13, v14, v15
	v_cvt_pk_bf16_f32 v14, v4, v5
	v_cvt_pk_bf16_f32 v15, v6, v7
	s_andn2_b64 vcc, exec, s[4:5]
	s_mov_b64 s[4:5], -1
	global_store_dwordx4 v187, v[12:15], s[16:17]
	s_cbranch_vccnz .LBB0_949
	s_andn2_b64 vcc, exec, s[2:3]
	s_cbranch_vccnz .LBB0_948
	s_barrier
	s_branch .LBB0_948
